# cand2 shifted by 1 s_nop at entry (code placement check)
# speedup vs baseline: 1.0024x; 1.0015x over previous
; #define LAS __attribute__((address_space(3)))
; __global__ void __launch_bounds__(NWAVES * 64, 2) skel_fwd(Args args) {
;     ...
;     F.lds = (LAS unsigned char*)lds;
;     F.MISC = (volatile LAS unsigned*)(F.lds + MISC_OFF);
;     F.tid = threadIdx.x; F.lane = F.tid & 63; F.wave = __builtin_amdgcn_readfirstlane(F.tid >> 6);
;     F.G = gridDim.x; { const int bx = blockIdx.x; F.vcu = (F.G % 8 == 0) ? (bx % 8) * (F.G / 8) + bx / 8 : bx; }
_Z8skel_fwd4Args:
	s_nop 0
	s_load_dword s76, s[0:1], 0x98
	s_mov_b32 s73, s2
	s_add_u32 s2, s0, 0x98
	s_addc_u32 s3, s1, 0
	s_mov_b32 s78, s73
	v_writelane_b32 v243, s2, 0
	s_nop 1
	v_writelane_b32 v243, s3, 1
	s_waitcnt lgkmcnt(0)
	s_and_b32 s2, s76, 7
	s_cmp_lg_u32 s2, 0
	s_cbranch_scc1 .LBB0_2
	s_ashr_i32 s3, s73, 31
	s_lshr_b32 s3, s3, 29
	s_add_i32 s3, s73, s3
	s_and_b32 s4, s3, -8
	s_ashr_i32 s2, s76, 3
	s_sub_i32 s4, s73, s4
	s_mul_i32 s2, s2, s4
	s_ashr_i32 s3, s3, 3
	s_add_i32 s78, s2, s3
